# Vt-projection GEMM epilogue: all 16 row scales fetched with the first column group (one wait) instead of a load+vmcnt(0) drain per group
# speedup vs baseline: 1.0027x; 1.0027x over previous
; __device__ __forceinline__ unsigned pk2(float lo, float hi) { const f2_t v = {lo, hi}; return __builtin_bit_cast(unsigned, __builtin_convertvector(v, bf2_t)); }
;   __device__ __forceinline__ void operator()(const f32x4 (&acc)[2][2][4][2], int pm, int pn, int wr, int wc, int fr, int fq, bf16_t* shm, int tid) const {
; #pragma unroll
;     for (int bj = 0; bj < 2; ++bj)
; #pragma unroll
;       for (int n = 0; n < 2; ++n) {
;         asm volatile("" ::: "memory");
;         const int col = pn * 256 + bj * 128 + wc * 32 + n * 16 + fq * 4;
;         int b, key; if (col < NLAT) { b = col >> 11; key = col & 2047; } else { b = (col - NLAT) >> 8; key = 2048 + ((col - NLAT) & 255); }
;         const float s0 = rstd[2 * col + 1], s1 = rstd[2 * col + 3], s2 = rstd[2 * col + 5], s3 = rstd[2 * col + 7];
;         bf16_t* base = Vt + ((long)(b * 512 + pm * 256 + wr * 64 + fr)) * 2304 + key;
; #pragma unroll
;         for (int ai = 0; ai < 2; ++ai)
; #pragma unroll
;           for (int m = 0; m < 4; ++m) {
;             const f32x4 v = acc[ai][bj][m][n];
;             u32x2 w; w.x = pk2(v[0] * s0, v[1] * s1); w.y = pk2(v[2] * s2, v[3] * s3);
;             *(u32x2*)(base + (long)(ai * 128 + m * 16) * 2304) = w;
;           }
.LBB0_825:
	s_add_i32 s10, s14, 0xffff0000
	s_lshl_b32 s15, s15, 8
	s_lshr_b32 s17, s10, 8
	s_lshr_b32 s18, s13, 3
	s_cmpk_lt_u32 s13, 0x100
	s_nop 15
	s_nop 15
	v_mbcnt_lo_u32_b32 v0, -1, 0
	v_mbcnt_hi_u32_b32 v0, -1, v0
	s_cselect_b64 vcc, -1, 0
	v_mov_b32_e32 v0, 0x76c
	s_and_b64 s[10:11], vcc, exec
	v_or_b32_e32 v154, s14, v150
	v_bitop3_b32 v0, s14, v0, v150 bitop3:0xc8
	s_cselect_b32 s10, s18, s17
	v_readlane_b32 s16, v253, 7
	v_cndmask_b32_e32 v136, v152, v0, vcc
	v_lshlrev_b32_e32 v0, 1, v154
	v_readlane_b32 s28, v253, 19
	v_readlane_b32 s29, v253, 20
	s_lshl_b32 s10, s10, 9
	v_readlane_b32 s20, v253, 11
	v_lshl_add_u64 v[130:131], v[0:1], 2, s[28:29]
	global_load_dword v134, v[130:131], off offset:4
	global_load_dword v135, v[130:131], off offset:12
	global_load_dword v132, v[130:131], off offset:20
	global_load_dword v133, v[130:131], off offset:28
	global_load_dword v176, v[130:131], off offset:132
	global_load_dword v177, v[130:131], off offset:140
	global_load_dword v178, v[130:131], off offset:148
	global_load_dword v179, v[130:131], off offset:156
	global_load_dword v180, v[130:131], off offset:1028
	global_load_dword v181, v[130:131], off offset:1036
	global_load_dword v182, v[130:131], off offset:1044
	global_load_dword v183, v[130:131], off offset:1052
	global_load_dword v184, v[130:131], off offset:1156
	global_load_dword v185, v[130:131], off offset:1164
	global_load_dword v186, v[130:131], off offset:1172
	global_load_dword v187, v[130:131], off offset:1180
	v_readlane_b32 s21, v253, 12
	s_add_i32 s10, s10, s15
	v_add_u32_e32 v0, s10, v151
	v_mov_b64_e32 v[130:131], s[20:21]
	v_mad_i64_i32 v[130:131], s[10:11], v0, s57, v[130:131]
	v_lshlrev_b32_e32 v0, 1, v136
	v_lshl_add_u64 v[136:137], v[130:131], 0, v[0:1]
	s_mov_b32 s13, 0x12000
	s_mov_b32 s14, 0xb4000
	v_or_b32_e32 v0, 16, v154
	v_lshlrev_b32_e32 v0, 1, v0
	s_mov_b32 s15, s2
	v_readlane_b32 s17, v253, 8
	v_readlane_b32 s18, v253, 9
	v_readlane_b32 s19, v253, 10
	v_readlane_b32 s22, v253, 13
	v_readlane_b32 s23, v253, 14
	v_readlane_b32 s24, v253, 15
	v_readlane_b32 s25, v253, 16
	v_readlane_b32 s26, v253, 17
	v_readlane_b32 s27, v253, 18
	v_readlane_b32 s30, v253, 21
	v_readlane_b32 s31, v253, 22
	s_waitcnt vmcnt(0)
	v_pk_mul_f32 v[122:123], v[122:123], v[134:135]
	s_nop 0
	v_cvt_pk_bf16_f32 v122, v122, v123
	v_pk_mul_f32 v[124:125], v[124:125], v[132:133]
	v_pk_mul_f32 v[118:119], v[118:119], v[134:135]
	v_cvt_pk_bf16_f32 v123, v124, v125
	v_add_co_u32_e64 v124, s[10:11], s13, v136
	v_pk_mul_f32 v[120:121], v[120:121], v[132:133]
	s_nop 0
	v_addc_co_u32_e64 v125, s[10:11], 0, v137, s[10:11]
	v_cvt_pk_bf16_f32 v118, v118, v119
	v_cvt_pk_bf16_f32 v119, v120, v121
	v_add_co_u32_e64 v120, s[10:11], s58, v136
	v_pk_mul_f32 v[110:111], v[110:111], v[134:135]
	s_nop 0
	v_addc_co_u32_e64 v121, s[10:11], 0, v137, s[10:11]
	v_pk_mul_f32 v[112:113], v[112:113], v[132:133]
	v_cvt_pk_bf16_f32 v110, v110, v111
	v_cvt_pk_bf16_f32 v111, v112, v113
	v_add_co_u32_e64 v112, s[10:11], s59, v136
	v_pk_mul_f32 v[106:107], v[106:107], v[134:135]
	s_nop 0
	v_addc_co_u32_e64 v113, s[10:11], 0, v137, s[10:11]
	global_store_dwordx2 v[112:113], v[110:111], off
	v_pk_mul_f32 v[110:111], v[114:115], v[134:135]
	v_pk_mul_f32 v[112:113], v[116:117], v[132:133]
	v_cvt_pk_bf16_f32 v110, v110, v111
	v_cvt_pk_bf16_f32 v111, v112, v113
	v_add_co_u32_e64 v112, s[10:11], s60, v136
	v_pk_mul_f32 v[108:109], v[108:109], v[132:133]
	s_nop 0
	v_addc_co_u32_e64 v113, s[10:11], 0, v137, s[10:11]
	v_cvt_pk_bf16_f32 v106, v106, v107
	v_cvt_pk_bf16_f32 v107, v108, v109
	v_add_co_u32_e64 v108, s[10:11], s61, v136
	v_pk_mul_f32 v[102:103], v[102:103], v[134:135]
	s_nop 0
	v_addc_co_u32_e64 v109, s[10:11], 0, v137, s[10:11]
	v_pk_mul_f32 v[104:105], v[104:105], v[132:133]
	v_cvt_pk_bf16_f32 v102, v102, v103
	v_cvt_pk_bf16_f32 v103, v104, v105
	v_add_co_u32_e64 v104, s[10:11], s14, v136
	v_pk_mul_f32 v[98:99], v[98:99], v[134:135]
	s_nop 0
	v_addc_co_u32_e64 v105, s[10:11], 0, v137, s[10:11]
	v_pk_mul_f32 v[100:101], v[100:101], v[132:133]
	v_cvt_pk_bf16_f32 v98, v98, v99
	v_cvt_pk_bf16_f32 v99, v100, v101
	v_add_co_u32_e64 v100, s[10:11], s56, v136
	v_pk_mul_f32 v[126:127], v[126:127], v[134:135]
	s_nop 0
	v_addc_co_u32_e64 v101, s[10:11], 0, v137, s[10:11]
	v_pk_mul_f32 v[128:129], v[128:129], v[132:133]
	s_movk_i32 s10, 0x77c
	v_cvt_pk_bf16_f32 v126, v126, v127
	v_cvt_pk_bf16_f32 v127, v128, v129
	global_store_dwordx2 v[100:101], v[98:99], off
	v_bitop3_b32 v98, v154, s10, 16 bitop3:0xc8
	s_movk_i32 s10, 0x7c
	global_store_dwordx2 v[136:137], v[126:127], off
	global_store_dwordx2 v[124:125], v[122:123], off
	global_store_dwordx2 v[120:121], v[118:119], off
	global_store_dwordx2 v[112:113], v[110:111], off
	global_store_dwordx2 v[108:109], v[106:107], off
	global_store_dwordx2 v[104:105], v[102:103], off
	v_bitop3_b32 v99, v154, s10, 16 bitop3:0xc8
	v_or_b32_e32 v99, 0x800, v99
	v_lshl_add_u64 v[100:101], v[0:1], 2, s[28:29]
	v_cndmask_b32_e32 v104, v99, v98, vcc
	v_mov_b32_e32 v102, v176
	v_mov_b32_e32 v103, v177
	v_mov_b32_e32 v98, v178
	v_mov_b32_e32 v99, v179
	v_lshlrev_b32_e32 v0, 1, v104
	v_lshl_add_u64 v[100:101], v[130:131], 0, v[0:1]
	v_or_b32_e32 v0, 0x80, v154
	v_lshlrev_b32_e32 v0, 1, v0
	v_pk_mul_f32 v[90:91], v[90:91], v[102:103]
	s_nop 0
	v_cvt_pk_bf16_f32 v90, v90, v91
	v_pk_mul_f32 v[92:93], v[92:93], v[98:99]
	v_pk_mul_f32 v[86:87], v[86:87], v[102:103]
	v_cvt_pk_bf16_f32 v91, v92, v93
	v_add_co_u32_e64 v92, s[10:11], s13, v100
	v_pk_mul_f32 v[88:89], v[88:89], v[98:99]
	s_nop 0
	v_addc_co_u32_e64 v93, s[10:11], 0, v101, s[10:11]
	v_cvt_pk_bf16_f32 v86, v86, v87
	v_cvt_pk_bf16_f32 v87, v88, v89
; __device__ __forceinline__ unsigned pk2(float lo, float hi) { const f2_t v = {lo, hi}; return __builtin_bit_cast(unsigned, __builtin_convertvector(v, bf2_t)); }
;   __device__ __forceinline__ void operator()(const f32x4 (&acc)[2][2][4][2], int pm, int pn, int wr, int wc, int fr, int fq, bf16_t* shm, int tid) const {
;     ...
;       for (int n = 0; n < 2; ++n) {
;         asm volatile("" ::: "memory");
;         const int col = pn * 256 + bj * 128 + wc * 32 + n * 16 + fq * 4;
;         int b, key; if (col < NLAT) { b = col >> 11; key = col & 2047; } else { b = (col - NLAT) >> 8; key = 2048 + ((col - NLAT) & 255); }
;         const float s0 = rstd[2 * col + 1], s1 = rstd[2 * col + 3], s2 = rstd[2 * col + 5], s3 = rstd[2 * col + 7];
;         bf16_t* base = Vt + ((long)(b * 512 + pm * 256 + wr * 64 + fr)) * 2304 + key;
; #pragma unroll
;         for (int ai = 0; ai < 2; ++ai)
; #pragma unroll
;           for (int m = 0; m < 4; ++m) {
;             const f32x4 v = acc[ai][bj][m][n];
;             u32x2 w; w.x = pk2(v[0] * s0, v[1] * s1); w.y = pk2(v[2] * s2, v[3] * s3);
;             *(u32x2*)(base + (long)(ai * 128 + m * 16) * 2304) = w;
;           }
	v_add_co_u32_e64 v88, s[10:11], s58, v100
	v_pk_mul_f32 v[78:79], v[78:79], v[102:103]
	s_nop 0
	v_addc_co_u32_e64 v89, s[10:11], 0, v101, s[10:11]
	v_pk_mul_f32 v[80:81], v[80:81], v[98:99]
	v_cvt_pk_bf16_f32 v78, v78, v79
	v_cvt_pk_bf16_f32 v79, v80, v81
	v_add_co_u32_e64 v80, s[10:11], s59, v100
	v_pk_mul_f32 v[74:75], v[74:75], v[102:103]
	s_nop 0
	v_addc_co_u32_e64 v81, s[10:11], 0, v101, s[10:11]
	global_store_dwordx2 v[80:81], v[78:79], off
	v_pk_mul_f32 v[78:79], v[82:83], v[102:103]
	v_pk_mul_f32 v[80:81], v[84:85], v[98:99]
	v_cvt_pk_bf16_f32 v78, v78, v79
	v_cvt_pk_bf16_f32 v79, v80, v81
	v_add_co_u32_e64 v80, s[10:11], s60, v100
	v_pk_mul_f32 v[76:77], v[76:77], v[98:99]
	s_nop 0
	v_addc_co_u32_e64 v81, s[10:11], 0, v101, s[10:11]
	v_cvt_pk_bf16_f32 v74, v74, v75
	v_cvt_pk_bf16_f32 v75, v76, v77
	v_add_co_u32_e64 v76, s[10:11], s61, v100
	v_pk_mul_f32 v[70:71], v[70:71], v[102:103]
	s_nop 0
	v_addc_co_u32_e64 v77, s[10:11], 0, v101, s[10:11]
	v_pk_mul_f32 v[72:73], v[72:73], v[98:99]
	v_cvt_pk_bf16_f32 v70, v70, v71
	v_cvt_pk_bf16_f32 v71, v72, v73
	v_add_co_u32_e64 v72, s[10:11], s14, v100
	v_pk_mul_f32 v[66:67], v[66:67], v[102:103]
	s_nop 0
	v_addc_co_u32_e64 v73, s[10:11], 0, v101, s[10:11]
	v_pk_mul_f32 v[68:69], v[68:69], v[98:99]
	v_cvt_pk_bf16_f32 v66, v66, v67
	v_cvt_pk_bf16_f32 v67, v68, v69
	v_add_co_u32_e64 v68, s[10:11], s56, v100
	v_pk_mul_f32 v[94:95], v[94:95], v[102:103]
	s_nop 0
	v_addc_co_u32_e64 v69, s[10:11], 0, v101, s[10:11]
	global_store_dwordx2 v[68:69], v[66:67], off
	s_movk_i32 s10, 0x7ec
	v_mov_b32_e32 v67, 0x80
	v_pk_mul_f32 v[96:97], v[96:97], v[98:99]
	v_bitop3_b32 v66, v154, s10, v67 bitop3:0xc8
	s_movk_i32 s10, 0xec
	v_cvt_pk_bf16_f32 v94, v94, v95
	v_cvt_pk_bf16_f32 v95, v96, v97
	v_bitop3_b32 v67, v154, s10, v67 bitop3:0xc8
	global_store_dwordx2 v[100:101], v[94:95], off
	global_store_dwordx2 v[92:93], v[90:91], off
	global_store_dwordx2 v[88:89], v[86:87], off
	global_store_dwordx2 v[80:81], v[78:79], off
	global_store_dwordx2 v[76:77], v[74:75], off
	global_store_dwordx2 v[72:73], v[70:71], off
	v_or_b32_e32 v67, 0x800, v67
	v_cndmask_b32_e32 v72, v67, v66, vcc
	v_lshl_add_u64 v[66:67], v[0:1], 2, s[28:29]
	v_mov_b32_e32 v70, v180
	v_mov_b32_e32 v71, v181
	v_mov_b32_e32 v68, v182
	v_mov_b32_e32 v69, v183
	v_lshlrev_b32_e32 v0, 1, v72
	v_lshl_add_u64 v[66:67], v[130:131], 0, v[0:1]
	v_or_b32_e32 v0, 0x90, v154
	v_lshlrev_b32_e32 v0, 1, v0
	v_pk_mul_f32 v[58:59], v[58:59], v[70:71]
	s_nop 0
	v_cvt_pk_bf16_f32 v58, v58, v59
	v_pk_mul_f32 v[60:61], v[60:61], v[68:69]
	v_pk_mul_f32 v[54:55], v[54:55], v[70:71]
	v_cvt_pk_bf16_f32 v59, v60, v61
	v_add_co_u32_e64 v60, s[10:11], s13, v66
	v_pk_mul_f32 v[56:57], v[56:57], v[68:69]
	s_nop 0
	v_addc_co_u32_e64 v61, s[10:11], 0, v67, s[10:11]
	v_cvt_pk_bf16_f32 v54, v54, v55
	v_cvt_pk_bf16_f32 v55, v56, v57
	v_add_co_u32_e64 v56, s[10:11], s58, v66
	v_pk_mul_f32 v[46:47], v[46:47], v[70:71]
	s_nop 0
	v_addc_co_u32_e64 v57, s[10:11], 0, v67, s[10:11]
	v_pk_mul_f32 v[48:49], v[48:49], v[68:69]
	v_cvt_pk_bf16_f32 v46, v46, v47
	v_cvt_pk_bf16_f32 v47, v48, v49
	v_add_co_u32_e64 v48, s[10:11], s59, v66
	v_pk_mul_f32 v[42:43], v[42:43], v[70:71]
	s_nop 0
	v_addc_co_u32_e64 v49, s[10:11], 0, v67, s[10:11]
	global_store_dwordx2 v[48:49], v[46:47], off
	v_pk_mul_f32 v[46:47], v[50:51], v[70:71]
	v_pk_mul_f32 v[48:49], v[52:53], v[68:69]
	v_cvt_pk_bf16_f32 v46, v46, v47
	v_cvt_pk_bf16_f32 v47, v48, v49
	v_add_co_u32_e64 v48, s[10:11], s60, v66
	v_pk_mul_f32 v[44:45], v[44:45], v[68:69]
	s_nop 0
	v_addc_co_u32_e64 v49, s[10:11], 0, v67, s[10:11]
	v_cvt_pk_bf16_f32 v42, v42, v43
	v_cvt_pk_bf16_f32 v43, v44, v45
	v_add_co_u32_e64 v44, s[10:11], s61, v66
	v_pk_mul_f32 v[38:39], v[38:39], v[70:71]
; __device__ __forceinline__ unsigned pk2(float lo, float hi) { const f2_t v = {lo, hi}; return __builtin_bit_cast(unsigned, __builtin_convertvector(v, bf2_t)); }
; #define WAIT_V(n) asm volatile("s_waitcnt vmcnt(" #n ")" ::: "memory")
; template <bool OVL, bool PANEL = false, class Epi>
; __device__ __forceinline__ void gemm_phase(const bf16_t* __restrict__ A, long lda, const bf16_t* __restrict__ Bt, long ldb, int nM, int nN, int K,
;                                            const Epi& epi, bf16_t* shm, int w0) {
;     ...
;     if (OVL) WAIT_V(0);
;   __device__ __forceinline__ void operator()(const f32x4 (&acc)[2][2][4][2], int pm, int pn, int wr, int wc, int fr, int fq, bf16_t* shm, int tid) const {
;     ...
;       for (int n = 0; n < 2; ++n) {
;         asm volatile("" ::: "memory");
;         const int col = pn * 256 + bj * 128 + wc * 32 + n * 16 + fq * 4;
;         int b, key; if (col < NLAT) { b = col >> 11; key = col & 2047; } else { b = (col - NLAT) >> 8; key = 2048 + ((col - NLAT) & 255); }
;         const float s0 = rstd[2 * col + 1], s1 = rstd[2 * col + 3], s2 = rstd[2 * col + 5], s3 = rstd[2 * col + 7];
;         bf16_t* base = Vt + ((long)(b * 512 + pm * 256 + wr * 64 + fr)) * 2304 + key;
; #pragma unroll
;         for (int ai = 0; ai < 2; ++ai)
; #pragma unroll
;           for (int m = 0; m < 4; ++m) {
;             const f32x4 v = acc[ai][bj][m][n];
;             u32x2 w; w.x = pk2(v[0] * s0, v[1] * s1); w.y = pk2(v[2] * s2, v[3] * s3);
;             *(u32x2*)(base + (long)(ai * 128 + m * 16) * 2304) = w;
;           }
	s_nop 0
	v_addc_co_u32_e64 v45, s[10:11], 0, v67, s[10:11]
	v_pk_mul_f32 v[40:41], v[40:41], v[68:69]
	v_cvt_pk_bf16_f32 v38, v38, v39
	v_cvt_pk_bf16_f32 v39, v40, v41
	v_add_co_u32_e64 v40, s[10:11], s14, v66
	v_pk_mul_f32 v[34:35], v[34:35], v[70:71]
	s_nop 0
	v_addc_co_u32_e64 v41, s[10:11], 0, v67, s[10:11]
	v_pk_mul_f32 v[36:37], v[36:37], v[68:69]
	v_cvt_pk_bf16_f32 v34, v34, v35
	v_cvt_pk_bf16_f32 v35, v36, v37
	v_add_co_u32_e64 v36, s[10:11], s56, v66
	v_pk_mul_f32 v[62:63], v[62:63], v[70:71]
	s_nop 0
	v_addc_co_u32_e64 v37, s[10:11], 0, v67, s[10:11]
	global_store_dwordx2 v[36:37], v[34:35], off
	s_movk_i32 s10, 0x7fc
	v_mov_b32_e32 v35, 0x90
	v_pk_mul_f32 v[64:65], v[64:65], v[68:69]
	v_bitop3_b32 v34, v154, s10, v35 bitop3:0xc8
	s_movk_i32 s10, 0xfc
	v_cvt_pk_bf16_f32 v62, v62, v63
	v_cvt_pk_bf16_f32 v63, v64, v65
	v_bitop3_b32 v35, v154, s10, v35 bitop3:0xc8
	global_store_dwordx2 v[66:67], v[62:63], off
	global_store_dwordx2 v[60:61], v[58:59], off
	global_store_dwordx2 v[56:57], v[54:55], off
	global_store_dwordx2 v[48:49], v[46:47], off
	global_store_dwordx2 v[44:45], v[42:43], off
	global_store_dwordx2 v[40:41], v[38:39], off
	v_or_b32_e32 v35, 0x800, v35
	v_cndmask_b32_e32 v40, v35, v34, vcc
	v_lshl_add_u64 v[34:35], v[0:1], 2, s[28:29]
	v_mov_b32_e32 v38, v184
	v_mov_b32_e32 v39, v185
	v_mov_b32_e32 v36, v186
	v_mov_b32_e32 v37, v187
	v_lshlrev_b32_e32 v0, 1, v40
	v_lshl_add_u64 v[34:35], v[130:131], 0, v[0:1]
	v_pk_mul_f32 v[26:27], v[26:27], v[38:39]
	s_nop 0
	v_cvt_pk_bf16_f32 v26, v26, v27
	v_pk_mul_f32 v[28:29], v[28:29], v[36:37]
	v_pk_mul_f32 v[22:23], v[22:23], v[38:39]
	v_cvt_pk_bf16_f32 v27, v28, v29
	v_add_co_u32_e32 v28, vcc, s13, v34
	v_pk_mul_f32 v[24:25], v[24:25], v[36:37]
	s_nop 0
	v_addc_co_u32_e32 v29, vcc, 0, v35, vcc
	v_cvt_pk_bf16_f32 v22, v22, v23
	v_cvt_pk_bf16_f32 v23, v24, v25
	v_add_co_u32_e32 v24, vcc, s58, v34
	v_pk_mul_f32 v[14:15], v[14:15], v[38:39]
	s_nop 0
	v_addc_co_u32_e32 v25, vcc, 0, v35, vcc
	v_pk_mul_f32 v[16:17], v[16:17], v[36:37]
	v_cvt_pk_bf16_f32 v14, v14, v15
	v_cvt_pk_bf16_f32 v15, v16, v17
	v_add_co_u32_e32 v16, vcc, s59, v34
	v_pk_mul_f32 v[10:11], v[10:11], v[38:39]
	s_nop 0
	v_addc_co_u32_e32 v17, vcc, 0, v35, vcc
	global_store_dwordx2 v[16:17], v[14:15], off
	v_pk_mul_f32 v[14:15], v[18:19], v[38:39]
	v_pk_mul_f32 v[16:17], v[20:21], v[36:37]
	v_cvt_pk_bf16_f32 v14, v14, v15
	v_cvt_pk_bf16_f32 v15, v16, v17
	v_add_co_u32_e32 v16, vcc, s60, v34
	v_pk_mul_f32 v[12:13], v[12:13], v[36:37]
	s_nop 0
	v_addc_co_u32_e32 v17, vcc, 0, v35, vcc
	v_cvt_pk_bf16_f32 v10, v10, v11
	v_cvt_pk_bf16_f32 v11, v12, v13
	v_add_co_u32_e32 v12, vcc, s61, v34
	v_pk_mul_f32 v[6:7], v[6:7], v[38:39]
	s_nop 0
	v_addc_co_u32_e32 v13, vcc, 0, v35, vcc
	v_pk_mul_f32 v[8:9], v[8:9], v[36:37]
	v_cvt_pk_bf16_f32 v6, v6, v7
	v_cvt_pk_bf16_f32 v7, v8, v9
	v_add_co_u32_e32 v8, vcc, s14, v34
	v_pk_mul_f32 v[2:3], v[2:3], v[38:39]
	s_nop 0
	v_addc_co_u32_e32 v9, vcc, 0, v35, vcc
	v_pk_mul_f32 v[4:5], v[4:5], v[36:37]
	v_pk_mul_f32 v[30:31], v[30:31], v[38:39]
	v_pk_mul_f32 v[32:33], v[32:33], v[36:37]
	v_cvt_pk_bf16_f32 v2, v2, v3
	v_cvt_pk_bf16_f32 v3, v4, v5
	v_add_co_u32_e32 v4, vcc, 0xc6000, v34
	v_cvt_pk_bf16_f32 v30, v30, v31
	v_cvt_pk_bf16_f32 v31, v32, v33
	v_addc_co_u32_e32 v5, vcc, 0, v35, vcc
	global_store_dwordx2 v[34:35], v[30:31], off
	global_store_dwordx2 v[28:29], v[26:27], off
	global_store_dwordx2 v[24:25], v[22:23], off
	global_store_dwordx2 v[16:17], v[14:15], off
	global_store_dwordx2 v[12:13], v[10:11], off
	global_store_dwordx2 v[8:9], v[6:7], off
	global_store_dwordx2 v[4:5], v[2:3], off
	s_waitcnt vmcnt(0)
	s_andn2_b64 vcc, exec, s[8:9]
	s_mov_b32 s13, s12
	s_cbranch_vccz .LBB0_834
